# attention k-loop: one register copy per iteration instead of two (next block moved into the current-block registers once consumed; chain temporaries moved to the old holding registers)
# baseline (speedup 1.0000x reference)
.LBB0_170:
	s_nop 7
	v_cmp_le_f32_e32 vcc, 0, v47
	v_exp_f32_e64 v47, -|v47|
	s_nop 0
	v_add_f32_e32 v48, 1.0, v47
	v_rcp_f32_e32 v48, v48
	s_nop 0
	v_mul_f32_e32 v49, v47, v48
	v_cndmask_b32_e32 v47, v49, v48, vcc
	v_cndmask_b32_e32 v48, v48, v49, vcc
	v_cmp_le_f32_e32 vcc, 0, v46
	v_exp_f32_e64 v46, -|v46|
	v_cndmask_b32_e64 v48, 1.0, v48, s[70:71]
	v_cndmask_b32_e64 v47, 0, v47, s[70:71]
	v_add_f32_e32 v49, 1.0, v46
	v_rcp_f32_e32 v49, v49
	s_nop 0
	v_mul_f32_e32 v50, v46, v49
	v_cndmask_b32_e32 v46, v50, v49, vcc
	v_cndmask_b32_e32 v49, v49, v50, vcc
	v_cmp_le_f32_e32 vcc, 0, v45
	v_exp_f32_e64 v45, -|v45|
	v_cndmask_b32_e64 v49, 1.0, v49, s[68:69]
	v_mul_f32_e32 v49, v49, v48
	v_cndmask_b32_e64 v46, 0, v46, s[68:69]
	v_add_f32_e32 v50, 1.0, v45
	v_rcp_f32_e32 v50, v50
	s_nop 0
	v_mul_f32_e32 v51, v45, v50
	v_cndmask_b32_e32 v45, v51, v50, vcc
	v_cndmask_b32_e32 v50, v50, v51, vcc
	v_cmp_le_f32_e32 vcc, 0, v44
	v_exp_f32_e64 v44, -|v44|
	v_cndmask_b32_e64 v50, 1.0, v50, s[66:67]
	v_mul_f32_e32 v50, v50, v49
	v_cndmask_b32_e64 v45, 0, v45, s[66:67]
	v_add_f32_e32 v51, 1.0, v44
	v_rcp_f32_e32 v51, v51
	s_nop 0
	v_mul_f32_e32 v52, v44, v51
	v_cndmask_b32_e32 v44, v52, v51, vcc
	v_cndmask_b32_e32 v51, v51, v52, vcc
	v_cmp_le_f32_e32 vcc, 0, v43
	v_exp_f32_e64 v43, -|v43|
	v_cndmask_b32_e64 v51, 1.0, v51, s[64:65]
	v_mul_f32_e32 v51, v51, v50
	v_cndmask_b32_e64 v44, 0, v44, s[64:65]
	v_add_f32_e32 v52, 1.0, v43
	v_rcp_f32_e32 v52, v52
	s_nop 0
	v_mul_f32_e32 v53, v43, v52
	v_cndmask_b32_e32 v43, v53, v52, vcc
	v_cndmask_b32_e32 v52, v52, v53, vcc
	v_cmp_le_f32_e32 vcc, 0, v42
	v_exp_f32_e64 v42, -|v42|
	v_cndmask_b32_e64 v52, 1.0, v52, s[62:63]
	v_mul_f32_e32 v52, v52, v51
	v_cndmask_b32_e64 v43, 0, v43, s[62:63]
	v_add_f32_e32 v53, 1.0, v42
	v_rcp_f32_e32 v53, v53
	s_nop 0
	v_mul_f32_e32 v54, v42, v53
	v_cndmask_b32_e32 v42, v54, v53, vcc
	v_cndmask_b32_e32 v53, v53, v54, vcc
	v_cmp_le_f32_e32 vcc, 0, v41
	v_exp_f32_e64 v41, -|v41|
	v_cndmask_b32_e64 v53, 1.0, v53, s[60:61]
	v_mul_f32_e32 v53, v53, v52
	v_cndmask_b32_e64 v42, 0, v42, s[60:61]
	v_add_f32_e32 v54, 1.0, v41
	v_rcp_f32_e32 v54, v54
	s_nop 0
	v_mul_f32_e32 v55, v41, v54
	v_cndmask_b32_e32 v41, v55, v54, vcc
	v_cndmask_b32_e32 v54, v54, v55, vcc
	v_cmp_le_f32_e32 vcc, 0, v40
	v_exp_f32_e64 v40, -|v40|
	v_cndmask_b32_e64 v54, 1.0, v54, s[58:59]
	v_mul_f32_e32 v54, v54, v53
	v_cndmask_b32_e64 v41, 0, v41, s[58:59]
	v_add_f32_e32 v55, 1.0, v40
	v_rcp_f32_e32 v55, v55
	s_nop 0
	v_mul_f32_e32 v40, v40, v55
	v_cndmask_b32_e32 v56, v40, v55, vcc
	v_cndmask_b32_e32 v40, v55, v40, vcc
	v_cmp_le_f32_e32 vcc, 0, v39
	v_exp_f32_e64 v39, -|v39|
	v_cndmask_b32_e64 v40, 1.0, v40, s[56:57]
	v_cndmask_b32_e64 v56, 0, v56, s[56:57]
	v_add_f32_e32 v55, 1.0, v39
	v_rcp_f32_e32 v55, v55
	s_nop 0
	v_mul_f32_e32 v39, v39, v55
	v_cndmask_b32_e32 v57, v39, v55, vcc
	v_cndmask_b32_e32 v39, v55, v39, vcc
	v_cmp_le_f32_e32 vcc, 0, v38
	v_exp_f32_e64 v38, -|v38|
	v_cndmask_b32_e64 v39, 1.0, v39, s[54:55]
	v_cndmask_b32_e64 v57, 0, v57, s[54:55]
	v_add_f32_e32 v55, 1.0, v38
	v_rcp_f32_e32 v55, v55
	s_nop 0
	v_mul_f32_e32 v38, v38, v55
	v_cndmask_b32_e32 v58, v38, v55, vcc
	v_cndmask_b32_e32 v38, v55, v38, vcc
	v_cmp_le_f32_e32 vcc, 0, v37
	v_exp_f32_e64 v37, -|v37|
	v_cndmask_b32_e64 v38, 1.0, v38, s[52:53]
	v_mul_f32_e32 v38, v38, v39
	v_cndmask_b32_e64 v58, 0, v58, s[52:53]
	v_add_f32_e32 v55, 1.0, v37
	v_rcp_f32_e32 v55, v55
	s_nop 0
	v_mul_f32_e32 v37, v37, v55
	v_cndmask_b32_e32 v59, v37, v55, vcc
	v_cndmask_b32_e32 v37, v55, v37, vcc
	v_cmp_le_f32_e32 vcc, 0, v36
	v_exp_f32_e64 v36, -|v36|
	v_cndmask_b32_e64 v37, 1.0, v37, s[50:51]
	v_mul_f32_e32 v37, v37, v38
	v_cndmask_b32_e64 v59, 0, v59, s[50:51]
	v_add_f32_e32 v55, 1.0, v36
	v_rcp_f32_e32 v55, v55
	s_nop 0
	v_mul_f32_e32 v36, v36, v55
	v_cndmask_b32_e32 v60, v36, v55, vcc
	v_cndmask_b32_e32 v36, v55, v36, vcc
	v_cmp_le_f32_e32 vcc, 0, v35
	v_exp_f32_e64 v35, -|v35|
	v_cndmask_b32_e64 v36, 1.0, v36, s[48:49]
	v_mul_f32_e32 v36, v36, v37
	v_cndmask_b32_e64 v60, 0, v60, s[48:49]
	v_add_f32_e32 v55, 1.0, v35
	v_rcp_f32_e32 v55, v55
	s_nop 0
	v_mul_f32_e32 v35, v35, v55
	v_cndmask_b32_e32 v61, v35, v55, vcc
	v_cndmask_b32_e32 v35, v55, v35, vcc
	v_cmp_le_f32_e32 vcc, 0, v34
	v_exp_f32_e64 v34, -|v34|
	v_cndmask_b32_e64 v35, 1.0, v35, s[46:47]
	v_mul_f32_e32 v35, v35, v36
	v_cndmask_b32_e64 v61, 0, v61, s[46:47]
	v_add_f32_e32 v55, 1.0, v34
	v_rcp_f32_e32 v55, v55
	s_nop 0
	v_mul_f32_e32 v34, v34, v55
	v_cndmask_b32_e32 v62, v34, v55, vcc
	v_cndmask_b32_e32 v34, v55, v34, vcc
	v_cmp_le_f32_e32 vcc, 0, v33
	v_exp_f32_e64 v33, -|v33|
	v_cndmask_b32_e64 v34, 1.0, v34, s[44:45]
	v_mul_f32_e32 v34, v34, v35
	v_cndmask_b32_e64 v62, 0, v62, s[44:45]
	v_add_f32_e32 v55, 1.0, v33
	v_rcp_f32_e32 v55, v55
	s_nop 0
	v_mul_f32_e32 v33, v33, v55
	v_cndmask_b32_e32 v63, v33, v55, vcc
	v_cndmask_b32_e32 v33, v55, v33, vcc
	v_cmp_le_f32_e32 vcc, 0, v32
	v_exp_f32_e64 v32, -|v32|
	v_cndmask_b32_e64 v33, 1.0, v33, s[42:43]
	v_mul_f32_e32 v33, v33, v34
	v_cndmask_b32_e64 v63, 0, v63, s[42:43]
	v_add_f32_e32 v55, 1.0, v32
	v_rcp_f32_e32 v55, v55
	s_nop 0
	v_mul_f32_e32 v32, v32, v55
	v_cndmask_b32_e32 v64, v32, v55, vcc
	v_cndmask_b32_e32 v32, v55, v32, vcc
	v_cndmask_b32_e64 v32, 1.0, v32, s[40:41]
	v_mul_f32_e32 v55, v32, v33
	v_mul_f32_e32 v32, v40, v54
	ds_bpermute_b32 v40, v245, v55
	ds_bpermute_b32 v65, v245, v32
	v_cndmask_b32_e64 v64, 0, v64, s[40:41]
	s_waitcnt lgkmcnt(0)
; #define LAS __attribute__((address_space(3)))
; __device__ __forceinline__ void mixer_unit(LAS unsigned char* lds, int unit, const bf16* P, bf16* Y, const float* conv_w, const float* sgu_norm, const float* sgu_w, const float* sgu_b, int tid, int wave, int lane) {
;     ...
;         for (int k0 = t0 + 32;; k0 -= 32) {
;             const bool doA = actA && (k0 <= t0);
;             f32x16 zB = {}, zA = {};
;             if (actB) {
; #pragma unroll
;                 for (int ks = 0; ks < 4; ++ks) zB = __builtin_amdgcn_mfma_f32_32x32x16_bf16(kfn[ks], Qs[(4 + ks) * 64 + lane], zB, 0, 0, 0); }
;             if (doA) {
; #pragma unroll
;                 for (int ks = 0; ks < 4; ++ks) zA = __builtin_amdgcn_mfma_f32_32x32x16_bf16(kfn[ks], Qs[ks * 64 + lane], zA, 0, 0, 0); }
; #pragma unroll
;             for (int i = 0; i < 4; ++i) { const int key = (lane >> 3) + 8 * i, c = lane & 7; *(LAS v4u*)(Vr + key * 96 + 8 * c) = vvn[i]; }
; #pragma unroll
;             for (int ks = 0; ks < 4; ++ks) kfn[ks] = kf2[ks];
; #pragma unroll
;             for (int i = 0; i < 4; ++i) vvn[i] = vv2[i];
;             if (k0 >= 64) { const bf16* kp = P + (size_t)(k0 - 64 + pr) * NIN + 1792 + hd * 64 + 8 * h;
; #pragma unroll
;                 for (int ks = 0; ks < 4; ++ks) kf2[ks] = *(const __attribute__((address_space(1))) bf16x8*)(kp + 16 * ks);
; #pragma unroll
;                 for (int i = 0; i < 4; ++i) vv2[i] = *(const __attribute__((address_space(1))) v4u*)(P + (size_t)(k0 - 64 + (lane >> 3) + 8 * i) * NIN + 2304 + hd * 64 + 8 * (lane & 7)); }
;             if (actB) { const bool dg = (k0 == t0 + 32); SB_CHAIN(zB, oacc[1][0], oacc[1][1], lsB, dg);
;                 if (__builtin_amdgcn_ballot_w64(lsB > 1e-37f) == 0ull) actB = false; }
;             if (doA) { const bool dg = (k0 == t0); SB_CHAIN(zA, oacc[0][0], oacc[0][1], lsA, dg);
;                 if (__builtin_amdgcn_ballot_w64(lsA > 1e-37f) == 0ull) actA = false; }
;             if (k0 < 32 || !(actA || actB)) break;
;         }
	v_mul_f32_e32 v68, v32, v65
	v_cndmask_b32_e64 v32, 1.0, v40, s[38:39]
	v_mul_f32_e32 v69, v32, v68
	v_mul_f32_e32 v32, v64, v33
	v_mul_f32_e32 v33, v63, v34
	v_mul_f32_e32 v32, v32, v69
	v_mul_f32_e32 v33, v33, v69
	v_cndmask_b32_e64 v67, 1.0, v65, s[38:39]
	v_cvt_pk_bf16_f32 v32, v32, v33
	v_mul_f32_e32 v33, v56, v54
	v_mul_f32_e32 v34, v41, v53
	v_mul_f32_e32 v33, v67, v33
	v_mul_f32_e32 v34, v67, v34
	v_cvt_pk_bf16_f32 v64, v33, v34
	v_mul_f32_e32 v33, v62, v35
	v_mul_f32_e32 v34, v61, v36
	v_mul_f32_e32 v33, v33, v69
	v_mul_f32_e32 v34, v34, v69
	v_cvt_pk_bf16_f32 v33, v33, v34
	v_mul_f32_e32 v34, v42, v52
	v_mul_f32_e32 v35, v43, v51
	v_mul_f32_e32 v34, v67, v34
	v_mul_f32_e32 v35, v67, v35
	v_cvt_pk_bf16_f32 v65, v34, v35
	v_mul_f32_e32 v34, v60, v37
	v_mul_f32_e32 v35, v59, v38
	v_mul_f32_e32 v34, v34, v69
	v_mul_f32_e32 v35, v35, v69
	v_cvt_pk_bf16_f32 v34, v34, v35
	v_mul_f32_e32 v35, v44, v50
	v_mul_f32_e32 v35, v35, v67
	v_mul_f32_e32 v36, v45, v49
	v_mul_f32_e32 v36, v36, v67
	v_cvt_pk_bf16_f32 v66, v35, v36
	v_mul_f32_e32 v35, v58, v39
	v_mul_f32_e32 v35, v35, v69
	v_mul_f32_e32 v36, v57, v69
	v_cvt_pk_bf16_f32 v35, v35, v36
	v_mul_f32_e32 v36, v46, v48
	v_mul_f32_e32 v36, v36, v67
	v_mul_f32_e32 v37, v47, v67
	v_cvt_pk_bf16_f32 v67, v36, v37
	v_mul_f32_e32 v36, v55, v40
	v_mul_f32_e32 v214, v36, v68
	ds_read_b64_tr_b16 v[36:37], v244
	ds_read_b64_tr_b16 v[38:39], v244 offset:768
	s_waitcnt lgkmcnt(0)
	v_mfma_f32_32x32x16_bf16 v[48:63], v[36:39], v[32:35], 0
	ds_read_b64_tr_b16 v[36:37], v244 offset:3072
	ds_read_b64_tr_b16 v[38:39], v244 offset:3840
	v_cmp_lt_f32_e32 vcc, s26, v214
	s_cmp_lg_u64 vcc, 0
	s_cselect_b64 s[8:9], -1, 0
	s_cmp_lg_u32 s2, 0
	s_cselect_b64 s[0:1], -1, 0
	s_or_b64 s[10:11], s[6:7], s[8:9]
	s_waitcnt lgkmcnt(0)
	v_mfma_f32_32x32x16_bf16 v[48:63], v[36:39], v[64:67], v[48:63]
	ds_read_b64_tr_b16 v[36:37], v244 offset:64
	ds_read_b64_tr_b16 v[38:39], v244 offset:832
	ds_read_b64_tr_b16 v[68:69], v244 offset:3136
	ds_read_b64_tr_b16 v[70:71], v244 offset:3904
	s_and_b64 s[0:1], s[0:1], s[10:11]
	s_andn2_b64 vcc, exec, s[0:1]
	s_waitcnt lgkmcnt(2)
	v_mfma_f32_32x32x16_bf16 v[32:47], v[36:39], v[32:35], 0
	s_waitcnt lgkmcnt(0)
	v_mfma_f32_32x32x16_bf16 v[32:47], v[68:71], v[64:67], v[32:47]
	s_cbranch_vccnz .LBB0_184
	v_lshl_add_u64 v[216:217], v[206:207], 1, s[20:21]
	s_mov_b32 s5, s28
	s_waitcnt vmcnt(0)
.LBB0_172:
	v_cndmask_b32_e64 v65, 0, 1, s[6:7]
	v_cmp_ne_u32_e64 s[42:43], 1, v65
	s_andn2_b64 vcc, exec, s[6:7]
	s_cbranch_vccnz .LBB0_174
	ds_read_b128 v[64:67], v242 offset:53248
	ds_read_b128 v[68:71], v242 offset:54272
	ds_read_b128 v[72:75], v242 offset:55296
	ds_read_b128 v[76:79], v242 offset:56320
	s_waitcnt lgkmcnt(3)
	v_mfma_f32_32x32x16_bf16 v[80:95], v[124:127], v[64:67], 0
	s_waitcnt lgkmcnt(2)
	v_mfma_f32_32x32x16_bf16 v[80:95], v[116:119], v[68:71], v[80:95]
	s_waitcnt lgkmcnt(1)
	v_mfma_f32_32x32x16_bf16 v[80:95], v[120:123], v[72:75], v[80:95]
	s_waitcnt lgkmcnt(0)
	v_mfma_f32_32x32x16_bf16 v[80:95], v[112:115], v[76:79], v[80:95]

; #define LAS __attribute__((address_space(3)))
; __device__ __forceinline__ void mixer_unit(LAS unsigned char* lds, int unit, const bf16* P, bf16* Y, const float* conv_w, const float* sgu_norm, const float* sgu_w, const float* sgu_b, int tid, int wave, int lane) {
;     ...
;             for (int i = 0; i < 4; ++i) { const int key = (lane >> 3) + 8 * i, c = lane & 7; *(LAS v4u*)(Vr + key * 96 + 8 * c) = vvn[i]; }
; #pragma unroll
;             for (int ks = 0; ks < 4; ++ks) kfn[ks] = kf2[ks];
; #pragma unroll
;             for (int i = 0; i < 4; ++i) vvn[i] = vv2[i];
.LBB0_176:
	ds_write_b128 v243, v[96:99]
	ds_write_b128 v243, v[100:103] offset:1536
	ds_write_b128 v243, v[104:107] offset:3072
	ds_write_b128 v243, v[108:111] offset:4608
	s_waitcnt vmcnt(4)
	v_mov_b64_e32 v[124:125], v[128:129]
	v_mov_b64_e32 v[126:127], v[130:131]
	v_mov_b64_e32 v[116:117], v[132:133]
	v_mov_b64_e32 v[118:119], v[134:135]
	v_mov_b64_e32 v[120:121], v[136:137]
	v_mov_b64_e32 v[122:123], v[138:139]
	v_mov_b64_e32 v[112:113], v[140:141]
	v_mov_b64_e32 v[114:115], v[142:143]
	s_waitcnt vmcnt(0)
	v_mov_b64_e32 v[96:97], v[144:145]
	v_mov_b64_e32 v[98:99], v[146:147]
	v_mov_b64_e32 v[100:101], v[148:149]
	v_mov_b64_e32 v[102:103], v[150:151]
	v_mov_b64_e32 v[104:105], v[152:153]
	v_mov_b64_e32 v[106:107], v[154:155]
	v_mov_b64_e32 v[108:109], v[156:157]
	v_mov_b64_e32 v[110:111], v[158:159]
	s_cmpk_lt_i32 s5, 0x60
	s_cbranch_scc0 .LBB0_182
	s_and_b64 vcc, exec, s[42:43]
	s_mov_b64 s[6:7], 0
	s_cbranch_vccz .LBB0_183

.LBB0_179:
	v_exp_f32_e64 v81, -|v79|
	v_exp_f32_e64 v80, -|v71|
	v_exp_f32_e64 v83, -|v78|
	v_exp_f32_e64 v85, -|v77|
	v_exp_f32_e64 v82, -|v70|
	v_exp_f32_e64 v87, -|v76|
	v_exp_f32_e64 v84, -|v69|
	v_add_f32_e32 v160, 1.0, v81
	v_exp_f32_e64 v89, -|v75|
	v_exp_f32_e64 v86, -|v68|
	v_rcp_f32_e32 v161, v160
	v_add_f32_e32 v160, 1.0, v80
	v_exp_f32_e64 v88, -|v67|
	v_rcp_f32_e32 v160, v160
	v_add_f32_e32 v162, 1.0, v83
	v_exp_f32_e64 v91, -|v74|
	v_exp_f32_e64 v93, -|v73|
	v_rcp_f32_e32 v163, v162
	v_add_f32_e32 v162, 1.0, v82
	v_cmp_le_f32_e64 s[0:1], 0, v78
	v_add_f32_e32 v78, 1.0, v85
	v_exp_f32_e64 v90, -|v66|
	v_exp_f32_e64 v92, -|v65|
	v_rcp_f32_e32 v162, v162
	v_cmp_le_f32_e32 vcc, 0, v79
	v_rcp_f32_e32 v79, v78
	v_add_f32_e32 v78, 1.0, v84
	v_add_f32_e32 v164, 1.0, v87
	v_exp_f32_e64 v95, -|v72|
	v_rcp_f32_e32 v78, v78
	v_rcp_f32_e32 v165, v164
	v_add_f32_e32 v164, 1.0, v86
	v_cmp_le_f32_e64 s[42:43], 0, v76
	v_add_f32_e32 v76, 1.0, v89
	v_exp_f32_e64 v94, -|v64|
	v_pk_mul_f32 v[80:81], v[80:81], v[160:161]
	v_rcp_f32_e32 v164, v164
	v_cmp_le_f32_e64 s[40:41], 0, v77
	v_rcp_f32_e32 v77, v76
	v_add_f32_e32 v76, 1.0, v88
	v_cndmask_b32_e32 v172, v81, v161, vcc
	v_rcp_f32_e32 v76, v76
	v_add_f32_e32 v166, 1.0, v91
	v_cmp_le_f32_e64 s[44:45], 0, v75
	v_add_f32_e32 v75, 1.0, v93
	v_cmp_le_f32_e64 s[46:47], 0, v73
	v_cndmask_b32_e32 v73, v161, v81, vcc
	v_cmp_le_f32_e32 vcc, 0, v71
	v_pk_mul_f32 v[82:83], v[82:83], v[162:163]
	v_rcp_f32_e32 v167, v166
	v_add_f32_e32 v166, 1.0, v90
	v_rcp_f32_e32 v169, v75
	v_add_f32_e32 v75, 1.0, v92
	v_cmp_le_f32_e64 s[48:49], 0, v72
	v_cndmask_b32_e32 v72, v160, v80, vcc
	v_cndmask_b32_e32 v160, v80, v160, vcc
	v_cmp_le_f32_e32 vcc, 0, v70
	v_pk_mul_f32 v[84:85], v[84:85], v[78:79]
	v_rcp_f32_e32 v166, v166
	v_rcp_f32_e32 v168, v75
	v_add_f32_e32 v75, 1.0, v95
	v_cndmask_b32_e32 v70, v162, v82, vcc
	v_cndmask_b32_e32 v80, v82, v162, vcc
	v_cmp_le_f32_e32 vcc, 0, v69
	v_pk_mul_f32 v[86:87], v[86:87], v[164:165]
	v_rcp_f32_e32 v171, v75
	v_add_f32_e32 v75, 1.0, v94
	v_cndmask_b32_e64 v71, v163, v83, s[0:1]
	v_cndmask_b32_e32 v82, v78, v84, vcc
	v_cndmask_b32_e32 v81, v84, v78, vcc
	v_cmp_le_f32_e32 vcc, 0, v68
	v_cndmask_b32_e64 v173, v83, v163, s[0:1]
	v_pk_mul_f32 v[88:89], v[88:89], v[76:77]
	v_rcp_f32_e32 v170, v75
	v_cndmask_b32_e64 v83, v79, v85, s[40:41]
	v_cndmask_b32_e32 v68, v164, v86, vcc
	v_cndmask_b32_e32 v86, v86, v164, vcc
	v_cmp_le_f32_e32 vcc, 0, v67
	v_pk_mul_f32 v[70:71], v[70:71], v[72:73]
	v_cndmask_b32_e64 v174, v85, v79, s[40:41]
	v_cndmask_b32_e64 v175, v87, v165, s[42:43]
	v_cndmask_b32_e64 v176, v89, v77, s[44:45]
	v_cndmask_b32_e64 v69, v165, v87, s[42:43]
	v_cndmask_b32_e64 v79, v77, v89, s[44:45]
	v_cndmask_b32_e32 v78, v76, v88, vcc
	v_cndmask_b32_e32 v87, v88, v76, vcc
	v_pk_mul_f32 v[76:77], v[82:83], v[70:71]
	v_pk_mul_f32 v[90:91], v[90:91], v[166:167]
	v_cmp_le_f32_e32 vcc, 0, v74
	v_cmp_le_f32_e64 s[0:1], 0, v66
	v_pk_mul_f32 v[68:69], v[68:69], v[76:77]
	v_pk_mul_f32 v[92:93], v[92:93], v[168:169]
	v_cndmask_b32_e32 v67, v167, v91, vcc
	v_cndmask_b32_e64 v66, v166, v90, s[0:1]
	v_cmp_le_f32_e64 s[40:41], 0, v65
	v_pk_mul_f32 v[78:79], v[78:79], v[68:69]
	v_pk_mul_f32 v[94:95], v[94:95], v[170:171]
	v_cndmask_b32_e64 v75, v169, v93, s[46:47]
	v_cndmask_b32_e64 v74, v168, v92, s[40:41]
	v_cmp_le_f32_e64 s[42:43], 0, v64
	v_pk_mul_f32 v[66:67], v[66:67], v[78:79]
	v_cndmask_b32_e64 v65, v171, v95, s[48:49]
	v_cndmask_b32_e64 v64, v170, v94, s[42:43]
	v_pk_mul_f32 v[74:75], v[74:75], v[66:67]
	v_cndmask_b32_e64 v177, v93, v169, s[46:47]
	v_pk_mul_f32 v[64:65], v[64:65], v[74:75]
	ds_bpermute_b32 v82, v245, v64
	ds_bpermute_b32 v83, v245, v65
	v_cndmask_b32_e64 v88, v90, v166, s[0:1]
	v_cndmask_b32_e64 v89, v92, v168, s[40:41]
	v_cndmask_b32_e64 v90, v94, v170, s[42:43]
	v_cndmask_b32_e64 v178, v95, v171, s[48:49]
	s_waitcnt lgkmcnt(1)
	v_cndmask_b32_e64 v92, 1.0, v82, s[38:39]
	s_waitcnt lgkmcnt(0)
	v_pk_mul_f32 v[84:85], v[64:65], v[82:83]
	v_mul_f32_e32 v82, v90, v74
	v_mul_f32_e32 v89, v89, v66
	v_mul_f32_e32 v90, v177, v67
	v_cndmask_b32_e64 v66, 1.0, v83, s[38:39]
	v_cndmask_b32_e32 v67, v91, v167, vcc
	v_mov_b32_e32 v215, v79
	v_mul_f32_e32 v64, v178, v75
	v_pk_mul_f32 v[74:75], v[214:215], v[66:67]
	v_mul_f32_e32 v65, v92, v85
	v_mul_f32_e32 v66, v74, v64
	v_mul_f32_e32 v64, v176, v69
	v_mul_f32_e32 v69, v74, v64
	v_mul_f32_e32 v64, v175, v77
	v_mul_f32_e32 v83, v64, v74
	v_mul_f32_e32 v64, v174, v71
	v_mul_f32_e32 v70, v81, v70
	v_mul_f32_e32 v71, v64, v74
	v_mov_b32_e32 v81, v214
	v_mov_b32_e32 v64, v72
	v_mul_f32_e32 v79, v86, v76
	v_pk_mul_f32 v[76:77], v[80:81], v[64:65]
	v_mul_f32_e32 v78, v88, v78
	v_mul_f32_e32 v68, v87, v68
	v_mul_f32_e32 v67, v74, v90
	v_mul_f32_e32 v64, v82, v77
	v_mul_f32_e32 v65, v89, v77
	v_cvt_pk_bf16_f32 v64, v64, v65
	v_mul_f32_e32 v65, v78, v77
	v_mul_f32_e32 v72, v68, v77
	v_cvt_pk_bf16_f32 v68, v66, v67
	v_mul_f32_e32 v66, v79, v77
	v_mul_f32_e32 v67, v70, v77
	v_mul_f32_e32 v75, v74, v75
	v_cvt_pk_bf16_f32 v65, v65, v72
	v_cvt_pk_bf16_f32 v69, v75, v69
	v_cvt_pk_bf16_f32 v66, v66, v67
	v_cvt_pk_bf16_f32 v70, v83, v71
	v_mul_f32_e32 v67, v76, v77
	v_mul_f32_e32 v71, v160, v77
	v_cvt_pk_bf16_f32 v67, v67, v71
	v_mul_f32_e32 v71, v173, v73
	v_mul_f32_e32 v71, v71, v74
	v_mul_f32_e32 v72, v172, v74
	v_cvt_pk_bf16_f32 v71, v71, v72
	ds_read_b64_tr_b16 v[72:73], v244
	ds_read_b64_tr_b16 v[74:75], v244 offset:768
	ds_read_b64_tr_b16 v[78:79], v244 offset:832
	ds_read_b64_tr_b16 v[76:77], v244 offset:64
	s_waitcnt lgkmcnt(2)
	v_mfma_f32_32x32x16_bf16 v[48:63], v[72:75], v[64:67], v[48:63]
	ds_read_b64_tr_b16 v[72:73], v244 offset:3072
	ds_read_b64_tr_b16 v[74:75], v244 offset:3840
	ds_read_b64_tr_b16 v[82:83], v244 offset:3904
	ds_read_b64_tr_b16 v[80:81], v244 offset:3136
	s_waitcnt lgkmcnt(4)
	v_mfma_f32_32x32x16_bf16 v[32:47], v[76:79], v[64:67], v[32:47]
	v_mul_f32_e32 v64, v84, v85
	v_mul_f32_e32 v214, v214, v64
	v_cmp_lt_f32_e32 vcc, s26, v214
	s_cmp_lg_u64 vcc, 0
	s_cselect_b64 s[8:9], -1, 0
	s_waitcnt lgkmcnt(2)
	v_mfma_f32_32x32x16_bf16 v[48:63], v[72:75], v[68:71], v[48:63]
	s_waitcnt lgkmcnt(0)
	v_mfma_f32_32x32x16_bf16 v[32:47], v[80:83], v[68:71], v[32:47]
; __device__ __forceinline__ void mixer_unit(LAS unsigned char* lds, int unit, const bf16* P, bf16* Y, const float* conv_w, const float* sgu_norm, const float* sgu_w, const float* sgu_b, int tid, int wave, int lane) {
;     ...
;             if (k0 >= 64) { const bf16* kp = P + (size_t)(k0 - 64 + pr) * NIN + 1792 + hd * 64 + 8 * h;
; #pragma unroll
;                 for (int ks = 0; ks < 4; ++ks) kf2[ks] = *(const __attribute__((address_space(1))) bf16x8*)(kp + 16 * ks);
; #pragma unroll
;                 for (int i = 0; i < 4; ++i) vv2[i] = *(const __attribute__((address_space(1))) v4u*)(P + (size_t)(k0 - 64 + (lane >> 3) + 8 * i) * NIN + 2304 + hd * 64 + 8 * (lane & 7)); }
;     ...
;             if (k0 < 32 || !(actA || actB)) break;
.LBB0_180:
	s_cmp_gt_i32 s5, 63
	s_cselect_b64 s[0:1], -1, 0
	s_or_b64 s[12:13], s[6:7], s[8:9]
	s_and_b64 s[0:1], s[0:1], s[12:13]
	s_and_b64 vcc, exec, s[0:1]
	s_cbranch_vccz .LBB0_184
	s_mov_b32 s5, s10
	s_branch .LBB0_172
.LBB0_182:
	v_add_u32_e32 v160, s5, v211
	v_add_u32_e32 v160, 0xffffffa0, v160
	v_mad_u64_u32 v[160:161], s[0:1], v160, s90, v[216:217]
	v_add_u32_e32 v166, s5, v241
	global_load_dwordx4 v[128:131], v[160:161], off offset:3584
	global_load_dwordx4 v[132:135], v[160:161], off offset:3616
	global_load_dwordx4 v[136:139], v[160:161], off offset:3648
	global_load_dwordx4 v[140:143], v[160:161], off offset:3680
	v_add_u32_e32 v162, 0xffffffa0, v166
	v_mov_b64_e32 v[160:161], s[22:23]
	v_mad_i64_i32 v[162:163], s[0:1], v162, s90, v[160:161]
	v_lshl_add_u64 v[162:163], v[162:163], 0, s[98:99]
	v_add_u32_e32 v164, 0xffffffa8, v166
	v_lshl_add_u64 v[162:163], v[162:163], 0, v[192:193]
	v_mad_i64_i32 v[164:165], s[0:1], v164, s90, v[160:161]
	v_add_co_u32_e32 v162, vcc, s91, v162
	v_lshl_add_u64 v[164:165], v[164:165], 0, s[98:99]
	s_nop 0
	v_addc_co_u32_e32 v163, vcc, 0, v163, vcc
	v_lshl_add_u64 v[164:165], v[164:165], 0, v[192:193]
	v_add_co_u32_e32 v164, vcc, s91, v164
	s_nop 1
	v_addc_co_u32_e32 v165, vcc, 0, v165, vcc
	global_load_dwordx4 v[144:147], v[162:163], off offset:512
	global_load_dwordx4 v[148:151], v[164:165], off offset:512
	v_add_u32_e32 v162, 0xffffffb0, v166
	v_mad_i64_i32 v[162:163], s[0:1], v162, s90, v[160:161]
	v_lshl_add_u64 v[162:163], v[162:163], 0, s[98:99]
	v_add_u32_e32 v164, 0xffffffb8, v166
	v_lshl_add_u64 v[162:163], v[162:163], 0, v[192:193]
	v_mad_i64_i32 v[160:161], s[0:1], v164, s90, v[160:161]
	v_add_co_u32_e32 v162, vcc, 0x1000, v162
	v_lshl_add_u64 v[160:161], v[160:161], 0, s[98:99]
	s_nop 0
	v_addc_co_u32_e32 v163, vcc, 0, v163, vcc
	v_lshl_add_u64 v[160:161], v[160:161], 0, v[192:193]
	v_add_co_u32_e32 v160, vcc, 0x1000, v160
	s_nop 1
	v_addc_co_u32_e32 v161, vcc, 0, v161, vcc
	global_load_dwordx4 v[152:155], v[162:163], off offset:512
	global_load_dwordx4 v[156:159], v[160:161], off offset:512
	s_and_b64 vcc, exec, s[42:43]
	s_mov_b64 s[6:7], 0
	s_cbranch_vccnz .LBB0_178
.LBB0_183:
	v_exp_f32_e64 v161, -|v95|
	v_exp_f32_e64 v163, -|v94|
	v_exp_f32_e64 v162, -|v87|
	v_exp_f32_e64 v160, -|v86|
	v_exp_f32_e64 v165, -|v93|
	v_exp_f32_e64 v167, -|v92|
	v_exp_f32_e64 v164, -|v85|
	v_exp_f32_e64 v169, -|v91|
	v_exp_f32_e64 v166, -|v84|
	v_add_f32_e32 v176, 1.0, v161
	v_add_f32_e32 v178, 1.0, v163
	v_exp_f32_e64 v171, -|v90|
	v_exp_f32_e64 v168, -|v83|
	v_rcp_f32_e32 v177, v176
	v_add_f32_e32 v176, 1.0, v160
	v_rcp_f32_e32 v179, v178
	v_add_f32_e32 v178, 1.0, v162
	v_exp_f32_e64 v173, -|v89|
	v_exp_f32_e64 v170, -|v82|
	v_rcp_f32_e32 v176, v176
	v_rcp_f32_e32 v178, v178
	v_cmp_le_f32_e64 s[0:1], 0, v94
	v_add_f32_e32 v94, 1.0, v165
	v_exp_f32_e64 v175, -|v88|
	v_exp_f32_e64 v172, -|v81|
	v_cmp_le_f32_e32 vcc, 0, v95
	v_rcp_f32_e32 v95, v94
	v_add_f32_e32 v94, 1.0, v164
	v_add_f32_e32 v180, 1.0, v167
	v_exp_f32_e64 v174, -|v80|
	v_rcp_f32_e32 v94, v94
	v_rcp_f32_e32 v181, v180
	v_add_f32_e32 v180, 1.0, v166
	v_cmp_le_f32_e64 s[44:45], 0, v92
	v_add_f32_e32 v92, 1.0, v169
	v_rcp_f32_e32 v180, v180
	v_cmp_le_f32_e64 s[42:43], 0, v93
	v_rcp_f32_e32 v93, v92
	v_add_f32_e32 v92, 1.0, v168
	v_add_f32_e32 v182, 1.0, v171
	v_pk_mul_f32 v[160:161], v[160:161], v[176:177]
	v_pk_mul_f32 v[162:163], v[162:163], v[178:179]
	v_rcp_f32_e32 v92, v92
	v_rcp_f32_e32 v183, v182
	v_add_f32_e32 v182, 1.0, v170
	v_cmp_le_f32_e64 s[48:49], 0, v90
	v_add_f32_e32 v90, 1.0, v173
	v_cndmask_b32_e32 v186, v161, v177, vcc
	v_cndmask_b32_e64 v187, v163, v179, s[0:1]
	v_rcp_f32_e32 v182, v182
	v_cmp_le_f32_e64 s[46:47], 0, v91
	v_rcp_f32_e32 v91, v90
	v_add_f32_e32 v90, 1.0, v172
	v_add_f32_e32 v184, 1.0, v175
	v_cmp_le_f32_e64 s[50:51], 0, v89
	v_cndmask_b32_e64 v89, v179, v163, s[0:1]
	v_cmp_le_f32_e64 s[0:1], 0, v87
	v_cndmask_b32_e32 v87, v177, v161, vcc
	v_cmp_le_f32_e32 vcc, 0, v86
	v_pk_mul_f32 v[164:165], v[164:165], v[94:95]
	v_rcp_f32_e32 v90, v90
	v_rcp_f32_e32 v185, v184
	v_add_f32_e32 v184, 1.0, v174
	v_cmp_le_f32_e64 s[52:53], 0, v88
	v_cndmask_b32_e64 v88, v178, v162, s[0:1]
	v_cndmask_b32_e32 v86, v176, v160, vcc
	v_cndmask_b32_e32 v212, v160, v176, vcc
	v_cmp_le_f32_e32 vcc, 0, v85
	v_pk_mul_f32 v[166:167], v[166:167], v[180:181]
	v_rcp_f32_e32 v184, v184
	v_cndmask_b32_e64 v178, v162, v178, s[0:1]
	v_cndmask_b32_e64 v161, v95, v165, s[42:43]
	v_cndmask_b32_e32 v160, v94, v164, vcc
	v_cndmask_b32_e32 v176, v164, v94, vcc
	v_cmp_le_f32_e32 vcc, 0, v84
	v_pk_mul_f32 v[162:163], v[86:87], v[88:89]
	v_pk_mul_f32 v[168:169], v[168:169], v[92:93]
	v_cndmask_b32_e64 v85, v181, v167, s[44:45]
	v_cndmask_b32_e32 v84, v180, v166, vcc
	v_cndmask_b32_e32 v166, v166, v180, vcc
	v_cmp_le_f32_e32 vcc, 0, v83
	v_pk_mul_f32 v[160:161], v[160:161], v[162:163]
	v_cndmask_b32_e64 v188, v165, v95, s[42:43]
	v_cndmask_b32_e64 v189, v167, v181, s[44:45]
	v_pk_mul_f32 v[170:171], v[170:171], v[182:183]
	v_cndmask_b32_e64 v95, v93, v169, s[46:47]
	v_cndmask_b32_e32 v94, v92, v168, vcc
	v_cndmask_b32_e32 v167, v168, v92, vcc
	v_cmp_le_f32_e32 vcc, 0, v82
	v_pk_mul_f32 v[84:85], v[84:85], v[160:161]
	v_pk_mul_f32 v[172:173], v[172:173], v[90:91]
	v_cndmask_b32_e64 v83, v183, v171, s[48:49]
	v_cndmask_b32_e32 v82, v182, v170, vcc
	v_cmp_le_f32_e64 s[0:1], 0, v81
	v_pk_mul_f32 v[94:95], v[94:95], v[84:85]
	v_cndmask_b32_e64 v190, v169, v93, s[46:47]
	v_pk_mul_f32 v[174:175], v[174:175], v[184:185]
	v_cndmask_b32_e64 v93, v91, v173, s[50:51]
	v_cndmask_b32_e64 v92, v90, v172, s[0:1]
	v_cmp_le_f32_e64 s[42:43], 0, v80
	v_pk_mul_f32 v[82:83], v[82:83], v[94:95]
	v_cndmask_b32_e64 v81, v185, v175, s[52:53]
	v_cndmask_b32_e64 v80, v184, v174, s[42:43]
	v_pk_mul_f32 v[92:93], v[92:93], v[82:83]
	v_cndmask_b32_e64 v191, v171, v183, s[48:49]
	v_pk_mul_f32 v[80:81], v[80:81], v[92:93]
	ds_bpermute_b32 v165, v245, v81
	ds_bpermute_b32 v164, v245, v80
	v_cndmask_b32_e64 v90, v172, v90, s[0:1]
	v_cndmask_b32_e64 v215, v173, v91, s[50:51]
	v_cndmask_b32_e64 v91, v174, v184, s[42:43]
	s_waitcnt lgkmcnt(1)
	v_cndmask_b32_e64 v89, 1.0, v165, s[38:39]
	v_mul_f32_e32 v168, v213, v89
	s_waitcnt lgkmcnt(0)
	v_cndmask_b32_e64 v89, 1.0, v164, s[38:39]
	v_pk_mul_f32 v[164:165], v[80:81], v[164:165]
	v_mul_f32_e32 v81, v90, v82
	v_mul_f32_e32 v90, v167, v84
	v_mul_f32_e32 v84, v191, v95
	v_cndmask_b32_e64 v246, v175, v185, s[52:53]
	v_mul_f32_e32 v89, v89, v165
	v_mul_f32_e32 v80, v91, v92
	v_mul_f32_e32 v91, v84, v168
	v_mul_f32_e32 v84, v190, v85
	v_cndmask_b32_e32 v86, v170, v182, vcc
	v_mul_f32_e32 v82, v246, v93
	v_mul_f32_e32 v85, v84, v168
	v_mul_f32_e32 v84, v189, v161
	v_pk_mul_f32 v[88:89], v[212:213], v[88:89]
	v_mul_f32_e32 v82, v82, v168
	v_mul_f32_e32 v83, v215, v83
	v_mul_f32_e32 v86, v86, v94
	v_mul_f32_e32 v94, v84, v168
	v_mul_f32_e32 v84, v188, v163
	v_mul_f32_e32 v80, v80, v89
	v_mul_f32_e32 v81, v81, v89
	v_mul_f32_e32 v83, v83, v168
	v_mul_f32_e32 v92, v166, v160
	v_mul_f32_e32 v93, v176, v162
	v_mul_f32_e32 v95, v84, v168
	v_cvt_pk_bf16_f32 v80, v80, v81
	v_cvt_pk_bf16_f32 v84, v82, v83
	v_mul_f32_e32 v81, v86, v89
	v_mul_f32_e32 v82, v90, v89
	v_cvt_pk_bf16_f32 v81, v81, v82
	v_mul_f32_e32 v82, v92, v89
	v_mul_f32_e32 v83, v93, v89
	v_cvt_pk_bf16_f32 v85, v91, v85
	v_cvt_pk_bf16_f32 v82, v82, v83
	v_mul_f32_e32 v83, v88, v89
	v_mul_f32_e32 v88, v178, v89
	v_mul_f32_e32 v87, v187, v87
	v_cvt_pk_bf16_f32 v86, v94, v95
	v_cvt_pk_bf16_f32 v83, v83, v88
	v_mul_f32_e32 v87, v87, v168
	v_mul_f32_e32 v88, v186, v168
	v_cvt_pk_bf16_f32 v87, v87, v88
	ds_read_b64_tr_b16 v[88:89], v244
	ds_read_b64_tr_b16 v[90:91], v244 offset:768
	ds_read_b64_tr_b16 v[94:95], v244 offset:832
	ds_read_b64_tr_b16 v[92:93], v244 offset:64
	s_waitcnt lgkmcnt(2)
	v_mfma_f32_32x32x16_bf16 v[0:15], v[88:91], v[80:83], v[0:15]
	ds_read_b64_tr_b16 v[88:89], v244 offset:3072
	ds_read_b64_tr_b16 v[90:91], v244 offset:3840
	ds_read_b64_tr_b16 v[162:163], v244 offset:3904
	ds_read_b64_tr_b16 v[160:161], v244 offset:3136
	s_waitcnt lgkmcnt(4)
	v_mfma_f32_32x32x16_bf16 v[16:31], v[92:95], v[80:83], v[16:31]
	v_mul_f32_e32 v80, v164, v165
	v_mul_f32_e32 v213, v213, v80
	v_cmp_lt_f32_e32 vcc, s26, v213
	s_cmp_lg_u64 vcc, 0
	s_cselect_b64 s[6:7], -1, 0
	s_waitcnt lgkmcnt(2)
	v_mfma_f32_32x32x16_bf16 v[0:15], v[88:91], v[84:87], v[0:15]
	s_waitcnt lgkmcnt(0)
	v_mfma_f32_32x32x16_bf16 v[16:31], v[160:163], v[84:87], v[16:31]
	s_and_b64 vcc, exec, s[40:41]
	s_cbranch_vccz .LBB0_179
	s_branch .LBB0_180
